# grid barrier seams 1..12 rewritten: static episode index, XCD last arriver adds to top counter, everyone polls the top counter (no generation words)
# speedup vs baseline: 1.0313x; 1.0048x over previous
.LBB0_186:
	s_waitcnt vmcnt(0)
	s_barrier
	s_mov_b64 s[4:5], exec
	v_readlane_b32 s6, v230, 5
	v_readlane_b32 s7, v230, 6
	s_and_b64 s[6:7], s[4:5], s[6:7]
	s_mov_b64 exec, s[6:7]
	s_cbranch_execz .LBB0_238
	s_waitcnt vmcnt(0) lgkmcnt(0)
	v_mov_b32_e32 v1, 0x20040
	ds_read_b32 v3, v1
	ds_read_b32 v4, v1 offset:4
	v_readlane_b32 s3, v230, 4
	s_nop 1
	s_lshl_b32 s3, s3, 8
	s_add_u32 s3, s3, 0x23901400
	v_mov_b32_e32 v1, s3
	v_mov_b32_e32 v2, 1
	global_atomic_add v2, v1, v2, s[26:27] sc0
	s_waitcnt lgkmcnt(0)
	v_readfirstlane_b32 s10, v3
	v_readfirstlane_b32 s11, v4
	s_nop 1
	s_mul_i32 s13, s10, 2
	s_mul_i32 s14, s11, 2
	v_mov_b32_e32 v1, 0x23903400
	s_mov_b32 s9, 0
	s_waitcnt vmcnt(0)
	v_readfirstlane_b32 s12, v2
	s_nop 1
	s_add_u32 s12, s12, 1
	s_cmp_eq_u32 s12, s13
	s_cbranch_scc0 .Lgb_poll_1
	buffer_wbl2 sc1
	v_mov_b32_e32 v2, 1
	s_waitcnt vmcnt(0)
	global_atomic_add v2, v1, v2, s[26:27] sc0
	s_waitcnt vmcnt(0)
	v_readfirstlane_b32 s12, v2
	s_nop 1
	s_add_u32 s12, s12, 1
	s_cmp_ge_u32 s12, s14
	s_cbranch_scc1 .Lgb_done_1
.Lgb_poll_1:
	global_load_dword v2, v1, s[26:27] sc1
	s_waitcnt vmcnt(0)
	v_readfirstlane_b32 s12, v2
	s_nop 1
	s_cmp_ge_u32 s12, s14
	s_cbranch_scc1 .Lgb_done_1
	s_add_u32 s9, s9, 1
	s_cmp_ge_u32 s9, 0x4000
	s_cbranch_scc1 .Lgb_done_1
	s_sleep 1
	s_branch .Lgb_poll_1
.Lgb_done_1:
	buffer_inv sc1
	s_waitcnt vmcnt(0)

.LBB0_256:
	s_waitcnt vmcnt(0)
	s_waitcnt lgkmcnt(0)
	s_barrier
	s_mov_b64 s[4:5], exec
	v_readlane_b32 s6, v230, 5
	v_readlane_b32 s7, v230, 6
	s_and_b64 s[6:7], s[4:5], s[6:7]
	s_mov_b64 exec, s[6:7]
	s_cbranch_execz .LBB0_308
	s_waitcnt vmcnt(0) lgkmcnt(0)
	v_mov_b32_e32 v1, 0x20040
	ds_read_b32 v3, v1
	ds_read_b32 v4, v1 offset:4
	v_readlane_b32 s3, v230, 4
	s_nop 1
	s_lshl_b32 s3, s3, 8
	s_add_u32 s3, s3, 0x23901400
	v_mov_b32_e32 v1, s3
	v_mov_b32_e32 v2, 1
	global_atomic_add v2, v1, v2, s[26:27] sc0
	s_waitcnt lgkmcnt(0)
	v_readfirstlane_b32 s10, v3
	v_readfirstlane_b32 s11, v4
	s_nop 1
	s_mul_i32 s13, s10, 3
	s_mul_i32 s14, s11, 3
	v_mov_b32_e32 v1, 0x23903400
	s_mov_b32 s9, 0
	s_waitcnt vmcnt(0)
	v_readfirstlane_b32 s12, v2
	s_nop 1
	s_add_u32 s12, s12, 1
	s_cmp_eq_u32 s12, s13
	s_cbranch_scc0 .Lgb_poll_2
	buffer_wbl2 sc1
	v_mov_b32_e32 v2, 1
	s_waitcnt vmcnt(0)
	global_atomic_add v2, v1, v2, s[26:27] sc0
	s_waitcnt vmcnt(0)
	v_readfirstlane_b32 s12, v2
	s_nop 1
	s_add_u32 s12, s12, 1
	s_cmp_ge_u32 s12, s14
	s_cbranch_scc1 .Lgb_done_2

.LBB0_343:
.LBB0_344:
	s_waitcnt vmcnt(0)
	s_waitcnt vmcnt(0)
	s_barrier
	s_mov_b64 s[4:5], exec
	v_readlane_b32 s6, v230, 5
	v_readlane_b32 s7, v230, 6
	s_and_b64 s[6:7], s[4:5], s[6:7]
	s_mov_b64 exec, s[6:7]
	s_cbranch_execz .LBB0_396
	s_waitcnt vmcnt(0) lgkmcnt(0)
	v_mov_b32_e32 v1, 0x20040
	ds_read_b32 v3, v1
	ds_read_b32 v4, v1 offset:4
	v_readlane_b32 s3, v230, 4
	s_nop 1
	s_lshl_b32 s3, s3, 8
	s_add_u32 s3, s3, 0x23901400
	v_mov_b32_e32 v1, s3
	v_mov_b32_e32 v2, 1
	global_atomic_add v2, v1, v2, s[26:27] sc0
	s_waitcnt lgkmcnt(0)
	v_readfirstlane_b32 s10, v3
	v_readfirstlane_b32 s11, v4
	s_nop 1
	s_mul_i32 s13, s10, 4
	s_mul_i32 s14, s11, 4
	v_mov_b32_e32 v1, 0x23903400
	s_mov_b32 s9, 0
	s_waitcnt vmcnt(0)
	v_readfirstlane_b32 s12, v2
	s_nop 1
	s_add_u32 s12, s12, 1
	s_cmp_eq_u32 s12, s13
	s_cbranch_scc0 .Lgb_poll_3
	buffer_wbl2 sc1
	v_mov_b32_e32 v2, 1
	s_waitcnt vmcnt(0)
	global_atomic_add v2, v1, v2, s[26:27] sc0
	s_waitcnt vmcnt(0)
	v_readfirstlane_b32 s12, v2
	s_nop 1
	s_add_u32 s12, s12, 1
	s_cmp_ge_u32 s12, s14
	s_cbranch_scc1 .Lgb_done_3

.LBB0_437:
	s_waitcnt vmcnt(0)
	s_waitcnt vmcnt(0)
	s_barrier
	s_mov_b64 s[4:5], exec
	v_readlane_b32 s6, v230, 5
	v_readlane_b32 s7, v230, 6
	s_and_b64 s[6:7], s[4:5], s[6:7]
	s_mov_b64 exec, s[6:7]
	s_cbranch_execz .LBB0_489
	s_waitcnt vmcnt(0) lgkmcnt(0)
	v_mov_b32_e32 v1, 0x20040
	ds_read_b32 v3, v1
	ds_read_b32 v4, v1 offset:4
	v_readlane_b32 s3, v230, 4
	s_nop 1
	s_lshl_b32 s3, s3, 8
	s_add_u32 s3, s3, 0x23901400
	v_mov_b32_e32 v1, s3
	v_mov_b32_e32 v2, 1
	global_atomic_add v2, v1, v2, s[26:27] sc0
	s_waitcnt lgkmcnt(0)
	v_readfirstlane_b32 s10, v3
	v_readfirstlane_b32 s11, v4
	s_nop 1
	s_mul_i32 s13, s10, 5
	s_mul_i32 s14, s11, 5
	v_mov_b32_e32 v1, 0x23903400
	s_mov_b32 s9, 0
	s_waitcnt vmcnt(0)
	v_readfirstlane_b32 s12, v2
	s_nop 1
	s_add_u32 s12, s12, 1
	s_cmp_eq_u32 s12, s13
	s_cbranch_scc0 .Lgb_poll_4
	buffer_wbl2 sc1
	v_mov_b32_e32 v2, 1
	s_waitcnt vmcnt(0)
	global_atomic_add v2, v1, v2, s[26:27] sc0
	s_waitcnt vmcnt(0)
	v_readfirstlane_b32 s12, v2
	s_nop 1
	s_add_u32 s12, s12, 1
	s_cmp_ge_u32 s12, s14
	s_cbranch_scc1 .Lgb_done_4

.LBB0_507:
	s_waitcnt vmcnt(0)
	s_waitcnt lgkmcnt(0)
	s_barrier
	s_mov_b64 s[4:5], exec
	v_readlane_b32 s6, v230, 5
	v_readlane_b32 s7, v230, 6
	s_and_b64 s[6:7], s[4:5], s[6:7]
	s_mov_b64 exec, s[6:7]
	s_cbranch_execz .LBB0_559
	s_waitcnt vmcnt(0) lgkmcnt(0)
	v_mov_b32_e32 v1, 0x20040
	ds_read_b32 v3, v1
	ds_read_b32 v4, v1 offset:4
	v_readlane_b32 s3, v230, 4
	s_nop 1
	s_lshl_b32 s3, s3, 8
	s_add_u32 s3, s3, 0x23901400
	v_mov_b32_e32 v1, s3
	v_mov_b32_e32 v2, 1
	global_atomic_add v2, v1, v2, s[26:27] sc0
	s_waitcnt lgkmcnt(0)
	v_readfirstlane_b32 s10, v3
	v_readfirstlane_b32 s11, v4
	s_nop 1
	s_mul_i32 s13, s10, 6
	s_mul_i32 s14, s11, 6
	v_mov_b32_e32 v1, 0x23903400
	s_mov_b32 s9, 0
	s_waitcnt vmcnt(0)
	v_readfirstlane_b32 s12, v2
	s_nop 1
	s_add_u32 s12, s12, 1
	s_cmp_eq_u32 s12, s13
	s_cbranch_scc0 .Lgb_poll_5
	buffer_wbl2 sc1
	v_mov_b32_e32 v2, 1
	s_waitcnt vmcnt(0)
	global_atomic_add v2, v1, v2, s[26:27] sc0
	s_waitcnt vmcnt(0)
	v_readfirstlane_b32 s12, v2
	s_nop 1
	s_add_u32 s12, s12, 1
	s_cmp_ge_u32 s12, s14
	s_cbranch_scc1 .Lgb_done_5

.LBB0_598:
	s_waitcnt vmcnt(0)
	s_waitcnt vmcnt(0)
	s_barrier
	s_mov_b64 s[4:5], exec
	v_readlane_b32 s6, v230, 5
	v_readlane_b32 s7, v230, 6
	s_and_b64 s[6:7], s[4:5], s[6:7]
	s_mov_b64 exec, s[6:7]
	s_cbranch_execz .LBB0_650
	s_waitcnt vmcnt(0) lgkmcnt(0)
	v_mov_b32_e32 v1, 0x20040
	ds_read_b32 v3, v1
	ds_read_b32 v4, v1 offset:4
	v_readlane_b32 s3, v230, 4
	s_nop 1
	s_lshl_b32 s3, s3, 8
	s_add_u32 s3, s3, 0x23901400
	v_mov_b32_e32 v1, s3
	v_mov_b32_e32 v2, 1
	global_atomic_add v2, v1, v2, s[26:27] sc0
	s_waitcnt lgkmcnt(0)
	v_readfirstlane_b32 s10, v3
	v_readfirstlane_b32 s11, v4
	s_nop 1
	s_mul_i32 s13, s10, 7
	s_mul_i32 s14, s11, 7
	v_mov_b32_e32 v1, 0x23903400
	s_mov_b32 s9, 0
	s_waitcnt vmcnt(0)
	v_readfirstlane_b32 s12, v2
	s_nop 1
	s_add_u32 s12, s12, 1
	s_cmp_eq_u32 s12, s13
	s_cbranch_scc0 .Lgb_poll_6
	buffer_wbl2 sc1
	v_mov_b32_e32 v2, 1
	s_waitcnt vmcnt(0)
	global_atomic_add v2, v1, v2, s[26:27] sc0
	s_waitcnt vmcnt(0)
	v_readfirstlane_b32 s12, v2
	s_nop 1
	s_add_u32 s12, s12, 1
	s_cmp_ge_u32 s12, s14
	s_cbranch_scc1 .Lgb_done_6

.LBB0_837:
	s_waitcnt vmcnt(0)
	s_barrier
	s_mov_b64 s[4:5], exec
	v_readlane_b32 s6, v230, 5
	v_readlane_b32 s7, v230, 6
	s_and_b64 s[6:7], s[4:5], s[6:7]
	s_mov_b64 exec, s[6:7]
	s_cbranch_execz .LBB0_889
	s_waitcnt vmcnt(0) lgkmcnt(0)
	v_mov_b32_e32 v1, 0x20040
	ds_read_b32 v3, v1
	ds_read_b32 v4, v1 offset:4
	v_readlane_b32 s3, v230, 4
	s_nop 1
	s_lshl_b32 s3, s3, 8
	s_add_u32 s3, s3, 0x23901400
	v_mov_b32_e32 v1, s3
	v_mov_b32_e32 v2, 1
	global_atomic_add v2, v1, v2, s[26:27] sc0
	s_waitcnt lgkmcnt(0)
	v_readfirstlane_b32 s10, v3
	v_readfirstlane_b32 s11, v4
	s_nop 1
	s_mul_i32 s13, s10, 8
	s_mul_i32 s14, s11, 8
	v_mov_b32_e32 v1, 0x23903400
	s_mov_b32 s9, 0
	s_waitcnt vmcnt(0)
	v_readfirstlane_b32 s12, v2
	s_nop 1
	s_add_u32 s12, s12, 1
	s_cmp_eq_u32 s12, s13
	s_cbranch_scc0 .Lgb_poll_7
	buffer_wbl2 sc1
	v_mov_b32_e32 v2, 1
	s_waitcnt vmcnt(0)
	global_atomic_add v2, v1, v2, s[26:27] sc0
	s_waitcnt vmcnt(0)
	v_readfirstlane_b32 s12, v2
	s_nop 1
	s_add_u32 s12, s12, 1
	s_cmp_ge_u32 s12, s14
	s_cbranch_scc1 .Lgb_done_7

.LBB0_915:
	s_waitcnt vmcnt(0)
	s_barrier
	s_mov_b64 s[4:5], exec
	v_readlane_b32 s6, v230, 5
	v_readlane_b32 s7, v230, 6
	s_and_b64 s[6:7], s[4:5], s[6:7]
	s_mov_b64 exec, s[6:7]
	s_cbranch_execz .LBB0_967
	s_waitcnt vmcnt(0) lgkmcnt(0)
	v_mov_b32_e32 v1, 0x20040
	ds_read_b32 v3, v1
	ds_read_b32 v4, v1 offset:4
	v_readlane_b32 s3, v230, 4
	s_nop 1
	s_lshl_b32 s3, s3, 8
	s_add_u32 s3, s3, 0x23901400
	v_mov_b32_e32 v1, s3
	v_mov_b32_e32 v2, 1
	global_atomic_add v2, v1, v2, s[26:27] sc0
	s_waitcnt lgkmcnt(0)
	v_readfirstlane_b32 s10, v3
	v_readfirstlane_b32 s11, v4
	s_nop 1
	s_mul_i32 s13, s10, 9
	s_mul_i32 s14, s11, 9
	v_mov_b32_e32 v1, 0x23903400
	s_mov_b32 s9, 0
	s_waitcnt vmcnt(0)
	v_readfirstlane_b32 s12, v2
	s_nop 1
	s_add_u32 s12, s12, 1
	s_cmp_eq_u32 s12, s13
	s_cbranch_scc0 .Lgb_poll_8
	buffer_wbl2 sc1
	v_mov_b32_e32 v2, 1
	s_waitcnt vmcnt(0)
	global_atomic_add v2, v1, v2, s[26:27] sc0
	s_waitcnt vmcnt(0)
	v_readfirstlane_b32 s12, v2
	s_nop 1
	s_add_u32 s12, s12, 1
	s_cmp_ge_u32 s12, s14
	s_cbranch_scc1 .Lgb_done_8

.LBB0_1008:
	s_waitcnt vmcnt(0)
	s_waitcnt vmcnt(0)
	s_barrier
	s_mov_b64 s[4:5], exec
	v_readlane_b32 s6, v230, 5
	v_readlane_b32 s7, v230, 6
	s_and_b64 s[6:7], s[4:5], s[6:7]
	s_mov_b64 exec, s[6:7]
	s_cbranch_execz .LBB0_1060
	s_waitcnt vmcnt(0) lgkmcnt(0)
	v_mov_b32_e32 v1, 0x20040
	ds_read_b32 v3, v1
	ds_read_b32 v4, v1 offset:4
	v_readlane_b32 s3, v230, 4
	s_nop 1
	s_lshl_b32 s3, s3, 8
	s_add_u32 s3, s3, 0x23901400
	v_mov_b32_e32 v1, s3
	v_mov_b32_e32 v2, 1
	global_atomic_add v2, v1, v2, s[26:27] sc0
	s_waitcnt lgkmcnt(0)
	v_readfirstlane_b32 s10, v3
	v_readfirstlane_b32 s11, v4
	s_nop 1
	s_mul_i32 s13, s10, 10
	s_mul_i32 s14, s11, 10
	v_mov_b32_e32 v1, 0x23903400
	s_mov_b32 s9, 0
	s_waitcnt vmcnt(0)
	v_readfirstlane_b32 s12, v2
	s_nop 1
	s_add_u32 s12, s12, 1
	s_cmp_eq_u32 s12, s13
	s_cbranch_scc0 .Lgb_poll_9
	buffer_wbl2 sc1
	v_mov_b32_e32 v2, 1
	s_waitcnt vmcnt(0)
	global_atomic_add v2, v1, v2, s[26:27] sc0
	s_waitcnt vmcnt(0)
	v_readfirstlane_b32 s12, v2
	s_nop 1
	s_add_u32 s12, s12, 1
	s_cmp_ge_u32 s12, s14
	s_cbranch_scc1 .Lgb_done_9

.LBB0_1078:
	s_waitcnt vmcnt(0)
	s_waitcnt lgkmcnt(0)
	s_barrier
	s_mov_b64 s[4:5], exec
	v_readlane_b32 s6, v230, 5
	v_readlane_b32 s7, v230, 6
	s_and_b64 s[6:7], s[4:5], s[6:7]
	s_mov_b64 exec, s[6:7]
	s_cbranch_execz .LBB0_1130
	s_waitcnt vmcnt(0) lgkmcnt(0)
	v_mov_b32_e32 v1, 0x20040
	ds_read_b32 v3, v1
	ds_read_b32 v4, v1 offset:4
	v_readlane_b32 s3, v230, 4
	s_nop 1
	s_lshl_b32 s3, s3, 8
	s_add_u32 s3, s3, 0x23901400
	v_mov_b32_e32 v1, s3
	v_mov_b32_e32 v2, 1
	global_atomic_add v2, v1, v2, s[26:27] sc0
	s_waitcnt lgkmcnt(0)
	v_readfirstlane_b32 s10, v3
	v_readfirstlane_b32 s11, v4
	s_nop 1
	s_mul_i32 s13, s10, 11
	s_mul_i32 s14, s11, 11
	v_mov_b32_e32 v1, 0x23903400
	s_mov_b32 s9, 0
	s_waitcnt vmcnt(0)
	v_readfirstlane_b32 s12, v2
	s_nop 1
	s_add_u32 s12, s12, 1
	s_cmp_eq_u32 s12, s13
	s_cbranch_scc0 .Lgb_poll_10
	buffer_wbl2 sc1
	v_mov_b32_e32 v2, 1
	s_waitcnt vmcnt(0)
	global_atomic_add v2, v1, v2, s[26:27] sc0
	s_waitcnt vmcnt(0)
	v_readfirstlane_b32 s12, v2
	s_nop 1
	s_add_u32 s12, s12, 1
	s_cmp_ge_u32 s12, s14
	s_cbranch_scc1 .Lgb_done_10

.LBB0_1167:
.LBB0_1168:
	s_waitcnt vmcnt(0)
	s_barrier
	s_mov_b64 s[4:5], exec
	v_readlane_b32 s6, v230, 5
	v_readlane_b32 s7, v230, 6
	s_and_b64 s[6:7], s[4:5], s[6:7]
	s_mov_b64 exec, s[6:7]
	s_cbranch_execz .LBB0_1220
	s_waitcnt vmcnt(0) lgkmcnt(0)
	v_mov_b32_e32 v1, 0x20040
	ds_read_b32 v3, v1
	ds_read_b32 v4, v1 offset:4
	v_readlane_b32 s3, v230, 4
	s_nop 1
	s_lshl_b32 s3, s3, 8
	s_add_u32 s3, s3, 0x23901400
	v_mov_b32_e32 v1, s3
	v_mov_b32_e32 v2, 1
	global_atomic_add v2, v1, v2, s[26:27] sc0
	s_waitcnt lgkmcnt(0)
	v_readfirstlane_b32 s10, v3
	v_readfirstlane_b32 s11, v4
	s_nop 1
	s_mul_i32 s13, s10, 12
	s_mul_i32 s14, s11, 12
	v_mov_b32_e32 v1, 0x23903400
	s_mov_b32 s9, 0
	s_waitcnt vmcnt(0)
	v_readfirstlane_b32 s12, v2
	s_nop 1
	s_add_u32 s12, s12, 1
	s_cmp_eq_u32 s12, s13
	s_cbranch_scc0 .Lgb_poll_11
	buffer_wbl2 sc1
	v_mov_b32_e32 v2, 1
	s_waitcnt vmcnt(0)
	global_atomic_add v2, v1, v2, s[26:27] sc0
	s_waitcnt vmcnt(0)
	v_readfirstlane_b32 s12, v2
	s_nop 1
	s_add_u32 s12, s12, 1
	s_cmp_ge_u32 s12, s14
	s_cbranch_scc1 .Lgb_done_11

.LBB0_1261:
	s_waitcnt vmcnt(0)
	s_waitcnt vmcnt(0)
	s_barrier
	s_mov_b64 s[4:5], exec
	v_readlane_b32 s6, v230, 5
	v_readlane_b32 s7, v230, 6
	s_and_b64 s[6:7], s[4:5], s[6:7]
	s_mov_b64 exec, s[6:7]
	s_cbranch_execz .LBB0_1313
	s_waitcnt vmcnt(0) lgkmcnt(0)
	v_mov_b32_e32 v1, 0x20040
	ds_read_b32 v3, v1
	ds_read_b32 v4, v1 offset:4
	v_readlane_b32 s3, v230, 4
	s_nop 1
	s_lshl_b32 s3, s3, 8
	s_add_u32 s3, s3, 0x23901400
	v_mov_b32_e32 v1, s3
	v_mov_b32_e32 v2, 1
	global_atomic_add v2, v1, v2, s[26:27] sc0
	s_waitcnt lgkmcnt(0)
	v_readfirstlane_b32 s10, v3
	v_readfirstlane_b32 s11, v4
	s_nop 1
	s_mul_i32 s13, s10, 13
	s_mul_i32 s14, s11, 13
	v_mov_b32_e32 v1, 0x23903400
	s_mov_b32 s9, 0
	s_waitcnt vmcnt(0)
	v_readfirstlane_b32 s12, v2
	s_nop 1
	s_add_u32 s12, s12, 1
	s_cmp_eq_u32 s12, s13
	s_cbranch_scc0 .Lgb_poll_12
	buffer_wbl2 sc1
	v_mov_b32_e32 v2, 1
	s_waitcnt vmcnt(0)
	global_atomic_add v2, v1, v2, s[26:27] sc0
	s_waitcnt vmcnt(0)
	v_readfirstlane_b32 s12, v2
	s_nop 1
	s_add_u32 s12, s12, 1
	s_cmp_ge_u32 s12, s14
	s_cbranch_scc1 .Lgb_done_12
